# attention main loop: static s_setprio 1 for waves 4-7 (younger half), on mhat-fold version
# speedup vs baseline: 1.0017x; 1.0017x over previous
; #define WAIT_BAR(N) asm volatile("s_waitcnt vmcnt(" #N ") lgkmcnt(0)\n\ts_barrier":::"memory")
;   #define DMA_K(t,slot) glds16(ksrc+(long)(t)*KVBLK*PQ,(unsigned)__builtin_amdgcn_readfirstlane(kdst+(slot)))
;   #define DMA_V(t,slot) glds16(vsrc+(long)(t)*KVBLK*PQ,(unsigned)__builtin_amdgcn_readfirstlane(vdst+(slot)))
;   #define CMASK(P0,P1,t) do{int jb_=(t)-(NT-4); if(jb_>=0)cmask(P0,P1,jb_,qrel,hi);}while(0)
;   #define START(P0,P1) do{ const float rm=rowmax(P0,P1); resc=false; \
;     { const float dl=rm; mhat=fadd_s(mhat,dl); \
;       _Pragma("unroll") for(int r=0;r<16;++r){P0[r]=fsub_s(P0[r],dl);P1[r]=fsub_s(P1[r],dl);} \
;       _Pragma("unroll") for(int r=0;r<16;++r)negm[r]=-mhat; asm volatile("":"+v"(negm)); } \
;     _Pragma("unroll") for(int r=0;r<16;++r)P0[r]=__builtin_amdgcn_exp2f(P0[r]); }while(0)
;   #define CMASK(P0,P1,t) do{}while(0)
;   #define CMASK(P0,P1,t) do{}while(0)
; template<int THRL> __device__ __forceinline__ void attn_unit128(int qb,const bf16*Qh,const bf16*__restrict__ Kh,const bf16*__restrict__ Vh,bf16*Oh,char*shm){
;     ...
;   const int vb0=(int)(lds0+L_V)+((lane>>4)&1)*32+(lane&3)*8+(4*hi+((lane&15)>>2))*64;
;   const char*Kbase=shm+L_K; bf16x8 kf[8];
;   const lds_cptr shm3=(lds_cptr)shm; const lds_cptr kp0=shm3+L_K+hi*1024+r32*16; const lds_cptr vp0=shm3+L_V+((lane>>4)&1)*32+(lane&3)*8+(4*hi+((lane&15)>>2))*64;
;   const lds_cptr qp=shm3+L_Q+wid*4096+lane*16;
;     ...
;   const int NT=(q0+QB)/KVBLK;
;   DMA_K(0,0);DMA_V(0,0);DMA_K(1,KSLOT);
;   #pragma unroll
;   for(int d0=0;d0<4;++d0)glds16(&Qw[(long)r32*PQ+d0*16+hi*8],(unsigned)__builtin_amdgcn_readfirstlane(qdst+d0*1024));
;   float mhat=0.f,l_reg=0.f;f32x16 o[4];o[0]=f32x16{};o[1]=f32x16{};o[2]=f32x16{};o[3]=f32x16{};
;   const f32x16 zero16=f32x16{};
;   const int qrel=wid*QBLK+r32;
;     ...
;   bool resc=false;
;     ...
;   f32x16 pA0,pA1,pB0,pB1;
;   int sl_prev=0,sl_cur=0,sl_next=KSLOT;
;     ...
;   DMA_K(2,2*KSLOT);
;   WAIT_BAR(1);
;   { bf16x8 q4[4];
;     #pragma unroll
;     for(int d0=0;d0<4;++d0)q4[d0]=QLD(d0);
;     qkt(pA0,pA1,Kbase,q4,zero16,r32,hi); }
;   asm volatile("s_nop 15\n\ts_nop 7":"+v"(pA0),"+v"(pA1));CMASK(pA0,pA1,0);
;   START(pA0,pA1);
;   _Pragma("unroll") for(int r=0;r<16;++r)pA1[r]=__builtin_amdgcn_exp2f(pA1[r]);
;   WAIT_BAR(0);
;   DMA_K(3,0);DMA_V(1,KSLOT);
;   ROT();
;   kload8(kf,kp0+sl_cur);
;   WAIT_BAR(3);
;   s16x4 vlo[16],vhi[16]; u32x4 pw0,pw1,pw2,pw3;
.LBB0_367:
	v_lshlrev_b32_e32 v35, 1, v34
	v_lshlrev_b32_e32 v215, 3, v34
	v_lshlrev_b32_e32 v34, 4, v34
	v_and_b32_e32 v218, 32, v35
	v_and_b32_e32 v34, 0xc0, v34
	v_and_b32_e32 v219, 24, v215
	v_lshl_or_b32 v217, v186, 8, v34
	v_add_u32_e32 v34, 0, v218
	v_add3_u32 v224, v34, v219, v217
	v_max3_f32 v34, v0, v1, v16
	v_max3_f32 v35, v2, v3, v17
	s_and_b32 s1, s1, 0x3fffffc0
	v_max3_f32 v34, v34, v18, v19
	v_max3_f32 v35, v35, v6, v7
	s_lshl_b32 s1, s1, 2
	v_max3_f32 v34, v34, v4, v5
	v_max3_f32 v35, v35, v22, v23
	s_add_i32 s34, s1, 0
	v_max3_f32 v34, v34, v20, v21
	v_max3_f32 v35, v35, v10, v11
	s_add_i32 s34, s34, 0x12000
	v_max3_f32 v34, v34, v8, v9
	v_max3_f32 v35, v35, v26, v27
	s_waitcnt vmcnt(0) lgkmcnt(0)
	s_barrier
	s_cmp_lg_u32 0, -1
	v_max3_f32 v34, v34, v24, v25
	v_max3_f32 v35, v35, v14, v15
	s_mov_b32 s72, 1
	v_max3_f32 v34, v34, v12, v13
	v_max3_f32 v35, v35, v30, v31
	s_mov_b32 s28, 0
	v_max3_f32 v34, v34, v28, v29
	v_lshlrev_b32_e32 v225, 4, v186
	v_max_f32_e32 v34, v34, v35
	v_lshl_add_u32 v216, v213, 2, s34
	v_mov_b32_e32 v35, v34
	s_nop 1
	v_permlane32_swap_b32_e32 v34, v35
	v_max_f32_e32 v34, v34, v35
	s_nop 0
	v_sub_f32_e32 v0, v0, v34
	v_sub_f32_e32 v1, v1, v34
	v_sub_f32_e32 v16, v16, v34
	v_sub_f32_e32 v17, v17, v34
	v_sub_f32_e32 v2, v2, v34
	v_sub_f32_e32 v18, v18, v34
	s_nop 0
	v_exp_f32_e32 v80, v0
	v_exp_f32_e32 v81, v1
	v_lshl_add_u64 v[0:1], v[180:181], 0, s[88:89]
	s_mov_b32 s1, m0
	s_mov_b32 m0, s42
	s_nop 0
	global_load_lds_dwordx4 v[0:1], off
	s_mov_b32 m0, s1
	s_cselect_b32 s1, 0, 0
	s_add_i32 s0, s1, s0
	v_lshl_add_u64 v[0:1], v[32:33], 0, s[86:87]
	s_add_i32 s1, s0, 0xa000
	s_mov_b32 s19, m0
	s_mov_b32 m0, s1
	s_nop 0
	global_load_lds_dwordx4 v[0:1], off
	s_mov_b32 m0, s19
	v_lshl_add_u64 v[0:1], v[32:33], 0, s[88:89]
	s_add_i32 s0, s0, 0xc000
	s_mov_b32 s1, m0
	s_mov_b32 m0, s0
	s_nop 0
	global_load_lds_dwordx4 v[0:1], off
	s_mov_b32 m0, s1
	ds_read_b128 v[168:171], v223 offset:8192
	ds_read_b128 v[160:163], v223 offset:8704
	ds_read_b128 v[172:175], v223 offset:10240
	ds_read_b128 v[156:159], v223 offset:10752
	ds_read_b128 v[164:167], v223 offset:12288
	ds_read_b128 v[148:151], v223 offset:12800
	ds_read_b128 v[152:155], v223 offset:14336
	ds_read_b128 v[144:147], v223 offset:14848
	v_sub_f32_e32 v3, v3, v34
	v_sub_f32_e32 v19, v19, v34
	v_sub_f32_e32 v4, v4, v34
	v_sub_f32_e32 v20, v20, v34
	v_sub_f32_e32 v5, v5, v34
	v_sub_f32_e32 v21, v21, v34
	v_sub_f32_e32 v6, v6, v34
	v_sub_f32_e32 v22, v22, v34
	v_sub_f32_e32 v7, v7, v34
	v_sub_f32_e32 v23, v23, v34
	v_sub_f32_e32 v8, v8, v34
	v_sub_f32_e32 v24, v24, v34
	v_sub_f32_e32 v9, v9, v34
	v_sub_f32_e32 v25, v25, v34
	v_sub_f32_e32 v10, v10, v34
	v_sub_f32_e32 v26, v26, v34
	v_sub_f32_e32 v11, v11, v34
	v_sub_f32_e32 v27, v27, v34
	v_sub_f32_e32 v12, v12, v34
	v_sub_f32_e32 v28, v28, v34
	v_sub_f32_e32 v13, v13, v34
	v_sub_f32_e32 v29, v29, v34
	v_sub_f32_e32 v14, v14, v34
	v_sub_f32_e32 v30, v30, v34
	v_sub_f32_e32 v15, v15, v34
	v_sub_f32_e32 v31, v31, v34
	v_exp_f32_e32 v82, v2
	v_exp_f32_e32 v83, v3
	v_exp_f32_e32 v84, v4
	v_exp_f32_e32 v85, v5
	v_exp_f32_e32 v86, v6
	v_exp_f32_e32 v87, v7
	v_exp_f32_e32 v88, v8
	v_exp_f32_e32 v89, v9
	v_exp_f32_e32 v90, v10
	v_exp_f32_e32 v91, v11
	v_exp_f32_e32 v92, v12
	v_exp_f32_e32 v93, v13
	v_exp_f32_e32 v94, v14
	v_exp_f32_e32 v95, v15
	v_exp_f32_e32 v64, v16
	v_exp_f32_e32 v65, v17
	v_exp_f32_e32 v66, v18
	v_exp_f32_e32 v67, v19
	v_exp_f32_e32 v68, v20
	v_exp_f32_e32 v69, v21
	v_exp_f32_e32 v70, v22
	v_exp_f32_e32 v71, v23
	v_exp_f32_e32 v72, v24
	v_exp_f32_e32 v73, v25
	v_exp_f32_e32 v74, v26
	v_exp_f32_e32 v75, v27
	v_exp_f32_e32 v76, v28
	v_exp_f32_e32 v77, v29
	v_exp_f32_e32 v78, v30
	v_exp_f32_e32 v79, v31
	s_waitcnt vmcnt(3) lgkmcnt(0)
	s_barrier
	s_andn2_b64 vcc, exec, s[16:17]
	v_cmp_gt_u32_e64 s[0:1], 32, v212
	v_add_f32_e32 v220, v195, v34
	s_cbranch_vccnz .LBB0_383
	s_add_u32 s20, s59, s24
	s_addc_u32 s21, s60, s25
	v_mov_b32_e32 v32, v195
	v_mov_b32_e32 v33, v195
	v_mov_b32_e32 v46, v195
	v_mov_b32_e32 v47, v195
	v_lshl_add_u64 v[182:183], s[20:21], 0, v[194:195]
	s_mov_b64 s[20:21], 0xa000
	v_mov_b32_e32 v34, v195
	v_mov_b32_e32 v35, v195
	v_mov_b32_e32 v36, v195
	v_mov_b32_e32 v37, v195
	v_mov_b32_e32 v38, v195
	v_mov_b32_e32 v39, v195
	v_mov_b32_e32 v40, v195
	v_mov_b32_e32 v41, v195
	v_mov_b32_e32 v42, v195
	v_mov_b32_e32 v43, v195
	v_mov_b32_e32 v44, v195
	v_mov_b32_e32 v45, v195
	v_mov_b64_e32 v[62:63], v[46:47]
	v_mov_b64_e32 v[16:17], v[32:33]
	v_mov_b64_e32 v[0:1], v[32:33]
	v_lshl_add_u64 v[184:185], v[180:181], 0, s[20:21]
	s_mov_b32 s20, 0
	s_movk_i32 s28, 0x4000
	s_movk_i32 s29, 0x2000
	v_mov_b32_e32 v226, 0
	s_mov_b32 s19, 6
	v_mov_b64_e32 v[60:61], v[44:45]
	v_mov_b64_e32 v[58:59], v[42:43]
	v_mov_b64_e32 v[56:57], v[40:41]
	v_mov_b64_e32 v[54:55], v[38:39]
	v_mov_b64_e32 v[52:53], v[36:37]
	v_mov_b64_e32 v[50:51], v[34:35]
	v_mov_b64_e32 v[48:49], v[32:33]
	v_mov_b64_e32 v[18:19], v[34:35]
	v_mov_b64_e32 v[20:21], v[36:37]
	v_mov_b64_e32 v[22:23], v[38:39]
	v_mov_b64_e32 v[24:25], v[40:41]
	v_mov_b64_e32 v[26:27], v[42:43]
	v_mov_b64_e32 v[28:29], v[44:45]
	v_mov_b64_e32 v[30:31], v[46:47]
	v_mov_b64_e32 v[2:3], v[34:35]
	v_mov_b64_e32 v[4:5], v[36:37]
	v_mov_b64_e32 v[6:7], v[38:39]
	v_mov_b64_e32 v[8:9], v[40:41]
	v_mov_b64_e32 v[10:11], v[42:43]
	v_mov_b64_e32 v[12:13], v[44:45]
	v_mov_b64_e32 v[14:15], v[46:47]
	v_add_u32_e32 v204, 0xfffed800, v222
	v_bfe_u32 v205, v204, 4, 6
	v_lshrrev_b32_e32 v204, 12, v204
	v_cmp_lt_u32_e64 s[98:99], 5, v204
	v_addc_co_u32_e64 v204, s[98:99], 0, v204, s[98:99]
	v_mul_u32_u24_e32 v204, 0xe00, v204
	v_lshl_add_u32 v189, v205, 2, v204
	v_add_u32_e32 v189, 0x1a800, v189
	ds_write_b32 v189, v192
	ds_write_b32 v189, v193 offset:256
	ds_write_b32 v189, v194 offset:512
	ds_write_b32 v189, v195 offset:768
	ds_write_b32 v189, v196 offset:1024
	ds_write_b32 v189, v197 offset:1280
	ds_write_b32 v189, v198 offset:1536
	ds_write_b32 v189, v199 offset:1792
	ds_write_b32 v189, v200 offset:2048
	ds_write_b32 v189, v201 offset:2304
	ds_write_b32 v189, v202 offset:2560
	ds_write_b32 v189, v203 offset:2816
	ds_write_b32 v189, v206 offset:3072
	ds_write_b32 v189, v207 offset:3328
	s_waitcnt lgkmcnt(0)
	v_add_u32_e32 v204, 0xfffed800, v222
	v_lshrrev_b32_e32 v204, 12, v204
	s_nop 0
	v_readfirstlane_b32 s98, v204
	s_cmp_gt_u32 s98, 3
	s_cbranch_scc0 .Lattn_prio_skip
	s_setprio 1
.Lattn_prio_skip:
	v_sub_f32_e32 v192, 0, v220
	v_sub_f32_e32 v193, 0, v220
	v_sub_f32_e32 v194, 0, v220
	v_sub_f32_e32 v195, 0, v220
	v_sub_f32_e32 v196, 0, v220
	v_sub_f32_e32 v197, 0, v220
	v_sub_f32_e32 v198, 0, v220
	v_sub_f32_e32 v199, 0, v220
	v_sub_f32_e32 v200, 0, v220
	v_sub_f32_e32 v201, 0, v220
	v_sub_f32_e32 v202, 0, v220
	v_sub_f32_e32 v203, 0, v220
	v_sub_f32_e32 v204, 0, v220
	v_sub_f32_e32 v205, 0, v220
	v_sub_f32_e32 v206, 0, v220
	v_sub_f32_e32 v207, 0, v220

; #define WAIT_BAR(N) asm volatile("s_waitcnt vmcnt(" #N ") lgkmcnt(0)\n\ts_barrier":::"memory")
;   #define RESC() do{ if(resc){ asm volatile("s_waitcnt lgkmcnt(0)":::"memory"); \
;       _Pragma("unroll") for(int d_=0;d_<2;++d_) _Pragma("unroll") for(int r=0;r<16;++r)o[d_][r]*=wsf[crow(r,hi)]; } }while(0)
;   #define ROT() do{sl_prev=sl_cur;sl_cur=sl_next;sl_next=(sl_next==(NSLOT-1)*SLOTB)?0:sl_next+SLOTB;}while(0)
;   #define ENDW(tt) do{ if((tt)+3<NT){WAIT_BAR(2);} else if((tt)+2<NT){WAIT_BAR(1);} else {WAIT_BAR(0);} }while(0)
; #define WAIT_BAR(N) asm volatile("s_waitcnt vmcnt(" #N ") lgkmcnt(0)\n\ts_barrier":::"memory")
;   #define RESC() do{ if(resc){ asm volatile("s_waitcnt lgkmcnt(0)":::"memory"); \
;       _Pragma("unroll") for(int d_=0;d_<4;++d_) _Pragma("unroll") for(int r=0;r<16;++r)o[d_][r]*=wsf[crow(r,hi)]; } }while(0)
;   #define ROT() do{sl_prev=sl_cur;sl_cur=sl_next;sl_next=(sl_next==(NSLOT-1)*KSLOT)?0:sl_next+KSLOT;}while(0)
;   #define ENDW(tt) do{ if((tt)+3<NT){WAIT_BAR(3);} else if((tt)+2<NT){WAIT_BAR(2);} else {WAIT_BAR(0);} }while(0)
; template<int THRL> __device__ __forceinline__ void attn_unit128(int qb,const bf16*Qh,const bf16*__restrict__ Kh,const bf16*__restrict__ Vh,bf16*Oh,char*shm){
;     ...
;   for(;t+5<NT;t+=2){
;     STEP(pB0,pB1,pA0,pA1,t,true,true,true);     WAIT_BAR(3); RESC(); ROT();
;     STEP(pA0,pA1,pB0,pB1,t+1,true,true,true);   WAIT_BAR(3); RESC(); ROT();
;   }
;     ...
;   for(;t+1<NT;t+=2){
;     STEP(pB0,pB1,pA0,pA1,t,(t+3<NT),(t+1<NT),(t+1<NT));       ENDW(t);   RESC(); ROT();
;     STEP(pA0,pA1,pB0,pB1,t+1,(t+4<NT),(t+2<NT),(t+2<NT));     ENDW(t+1); RESC(); ROT();
;   }
;   STEP(pB0,pB1,pA0,pA1,NT-1,false,false,false); RESC();
.LBB0_384:
	v_add_u32_e32 v204, 0xfffed800, v222
	v_bfe_u32 v205, v204, 4, 6
	v_lshrrev_b32_e32 v204, 12, v204
	v_cmp_lt_u32_e64 s[98:99], 5, v204
	v_addc_co_u32_e64 v204, s[98:99], 0, v204, s[98:99]
	v_mul_u32_u24_e32 v204, 0xe00, v204
	v_lshl_add_u32 v189, v205, 2, v204
	v_add_u32_e32 v189, 0x1a800, v189
	ds_read_b32 v192, v189
	ds_read_b32 v193, v189 offset:256
	ds_read_b32 v194, v189 offset:512
	ds_read_b32 v195, v189 offset:768
	ds_read_b32 v196, v189 offset:1024
	ds_read_b32 v197, v189 offset:1280
	ds_read_b32 v198, v189 offset:1536
	ds_read_b32 v199, v189 offset:1792
	ds_read_b32 v200, v189 offset:2048
	ds_read_b32 v201, v189 offset:2304
	ds_read_b32 v202, v189 offset:2560
	ds_read_b32 v203, v189 offset:2816
	ds_read_b32 v206, v189 offset:3072
	ds_read_b32 v207, v189 offset:3328
	s_waitcnt lgkmcnt(0)
	s_setprio 0
	s_add_i32 s72, s19, -3
